# v006 + per-unit scheduler: division by gsz (always 4) replaced by shift/and in all 9 GEMM phases
# speedup vs baseline: 1.0038x; 1.0038x over previous
;     __host__ __device__ bool next(int i, Unit& u) const {
;         const long L = (long)i * G + c; if (L >= nwg) return false;
;         int wgid = (int)L; { const int q = nwg / NXCD, r = nwg % NXCD, xcd = wgid % NXCD, off = wgid / NXCD; wgid = (xcd < r ? xcd * (q + 1) : r * (q + 1) + (xcd - r) * q) + off; }
;         const int nig = WGM * nN, gid = wgid / nig, fm = gid * WGM, gsz = (nM - fm) < WGM ? (nM - fm) : WGM;
;         u.pm = fm + ((wgid % nig) % gsz); u.pn = (wgid % nig) / gsz; return true;
;     }
.LBB0_212:
	s_add_i32 s46, s46, 1
	s_mul_i32 s4, s46, s47
	s_mul_hi_u32 s5, s46, s50
	s_add_i32 s5, s5, s4
	s_mul_i32 s4, s46, s50
	v_readlane_b32 s15, v239, 0
	s_add_u32 s18, s4, s15
	s_addc_u32 s19, s5, s36
	v_cmp_gt_i64_e32 vcc, s[18:19], v[144:145]
	v_cmp_lt_i64_e64 s[4:5], s[18:19], v[142:143]
	s_cbranch_vccnz .LBB0_214
	s_ashr_i32 s14, s18, 31
	s_lshr_b32 s14, s14, 29
	s_add_i32 s14, s18, s14
	s_ashr_i32 s15, s14, 3
	s_and_b32 s14, s14, -8
	s_sub_i32 s14, s18, s14
	s_cmp_lt_i32 s14, 0
	s_cselect_b32 s16, s37, 0x120
	s_mul_i32 s14, s14, s16
	s_add_i32 s14, s14, s15
	s_mul_hi_i32 s15, s14, 0x38e38e39
	s_lshr_b32 s16, s15, 31
	s_ashr_i32 s15, s15, 5
	s_add_i32 s15, s15, s16
	s_lshl_b32 s16, s15, 2
	s_sub_i32 s17, 64, s16
	s_min_i32 s17, s17, 4
	s_mulk_i32 s15, 0x90
	s_sub_i32 s15, s14, s15
	s_lshr_b32 s14, s15, 2
	s_and_b32 s15, s15, 3
	s_add_i32 s16, s16, s15

;     __host__ __device__ bool next(int i, Unit& u) const {
;         const long L = (long)i * G + c; if (L >= nwg) return false;
;         int wgid = (int)L; { const int q = nwg / NXCD, r = nwg % NXCD, xcd = wgid % NXCD, off = wgid / NXCD; wgid = (xcd < r ? xcd * (q + 1) : r * (q + 1) + (xcd - r) * q) + off; }
;         const int nig = WGM * nN, gid = wgid / nig, fm = gid * WGM, gsz = (nM - fm) < WGM ? (nM - fm) : WGM;
;         u.pm = fm + ((wgid % nig) % gsz); u.pn = (wgid % nig) / gsz; return true;
;     }
.LBB0_366:
	s_add_i32 s48, s48, 1
	s_mul_i32 s4, s48, s51
	s_mul_hi_u32 s5, s48, s52
	s_add_i32 s5, s5, s4
	s_mul_i32 s4, s48, s52
	v_readlane_b32 s15, v239, 0
	s_add_u32 s18, s4, s15
	s_addc_u32 s19, s5, s42
	v_cmp_gt_i64_e32 vcc, s[18:19], v[144:145]
	v_cmp_lt_i64_e64 s[4:5], s[18:19], v[142:143]
	s_cbranch_vccnz .LBB0_368
	s_ashr_i32 s14, s18, 31
	s_lshr_b32 s14, s14, 29
	s_add_i32 s14, s18, s14
	s_ashr_i32 s15, s14, 3
	s_and_b32 s14, s14, -8
	s_sub_i32 s14, s18, s14
	s_cmp_lt_i32 s14, 0
	s_cselect_b32 s16, s43, 0x120
	s_mul_i32 s14, s14, s16
	s_add_i32 s14, s14, s15
	s_mul_hi_i32 s15, s14, 0x38e38e39
	s_lshr_b32 s16, s15, 31
	s_ashr_i32 s15, s15, 5
	s_add_i32 s15, s15, s16
	s_lshl_b32 s16, s15, 2
	s_sub_i32 s17, 64, s16
	s_min_i32 s17, s17, 4
	s_mulk_i32 s15, 0x90
	s_sub_i32 s15, s14, s15
	s_lshr_b32 s14, s15, 2
	s_and_b32 s15, s15, 3
	s_add_i32 s16, s16, s15

;     __host__ __device__ bool next(int i, Unit& u) const {
;         const long L = (long)i * G + c; if (L >= nwg) return false;
;         int wgid = (int)L; { const int q = nwg / NXCD, r = nwg % NXCD, xcd = wgid % NXCD, off = wgid / NXCD; wgid = (xcd < r ? xcd * (q + 1) : r * (q + 1) + (xcd - r) * q) + off; }
;         const int nig = WGM * nN, gid = wgid / nig, fm = gid * WGM, gsz = (nM - fm) < WGM ? (nM - fm) : WGM;
;         u.pm = fm + ((wgid % nig) % gsz); u.pn = (wgid % nig) / gsz; return true;
;     }
.LBB0_583:
	s_ashr_i32 s18, s23, 3
	s_add_i32 s18, s24, s18
	s_ashr_i32 s19, s18, 31
	s_lshr_b32 s19, s19, 28
	s_add_i32 s19, s18, s19
	s_ashr_i32 s22, s19, 4
	s_lshl_b32 s22, s22, 2
	s_sub_i32 s23, 0x80, s22
	s_min_i32 s23, s23, 4
	s_and_b32 s19, s19, -16
	s_sub_i32 s19, s18, s19
	s_lshr_b32 s18, s19, 2
	s_and_b32 s19, s19, 3
	s_add_i32 s40, s22, s19

;     __host__ __device__ bool next(int i, Unit& u) const {
;         const long L = (long)i * G + c; if (L >= nwg) return false;
;         int wgid = (int)L; { const int q = nwg / NXCD, r = nwg % NXCD, xcd = wgid % NXCD, off = wgid / NXCD; wgid = (xcd < r ? xcd * (q + 1) : r * (q + 1) + (xcd - r) * q) + off; }
;         const int nig = WGM * nN, gid = wgid / nig, fm = gid * WGM, gsz = (nM - fm) < WGM ? (nM - fm) : WGM;
;         u.pm = fm + ((wgid % nig) % gsz); u.pn = (wgid % nig) / gsz; return true;
;     }
.LBB0_669:
	s_add_i32 s49, s49, 1
	s_mul_i32 s2, s49, s50
	s_mul_hi_u32 s3, s49, s53
	s_add_i32 s3, s3, s2
	s_mul_i32 s2, s49, s53
	v_readlane_b32 s15, v239, 0
	s_add_u32 s18, s2, s15
	s_addc_u32 s19, s3, s41
	v_cmp_gt_i64_e32 vcc, s[18:19], v[144:145]
	v_cmp_lt_i64_e64 s[2:3], s[18:19], v[142:143]
	s_cbranch_vccnz .LBB0_671
	s_ashr_i32 s14, s18, 31
	s_lshr_b32 s14, s14, 29
	s_add_i32 s14, s18, s14
	s_ashr_i32 s15, s14, 3
	s_and_b32 s14, s14, -8
	s_sub_i32 s14, s18, s14
	s_cmp_lt_i32 s14, 0
	s_cselect_b32 s16, s42, 0x160
	s_mul_i32 s14, s14, s16
	s_add_i32 s14, s14, s15
	s_mul_hi_i32 s15, s14, 0x2e8ba2e9
	s_lshr_b32 s16, s15, 31
	s_ashr_i32 s15, s15, 4
	s_add_i32 s15, s15, s16
	s_lshl_b32 s16, s15, 2
	s_sub_i32 s17, 0x80, s16
	s_min_i32 s17, s17, 4
	s_mulk_i32 s15, 0x58
	s_sub_i32 s15, s14, s15
	s_lshr_b32 s14, s15, 2
	s_and_b32 s15, s15, 3
	s_add_i32 s16, s16, s15

;     __host__ __device__ bool next(int i, Unit& u) const {
;         const long L = (long)i * G + c; if (L >= nwg) return false;
;         int wgid = (int)L; { const int q = nwg / NXCD, r = nwg % NXCD, xcd = wgid % NXCD, off = wgid / NXCD; wgid = (xcd < r ? xcd * (q + 1) : r * (q + 1) + (xcd - r) * q) + off; }
;         const int nig = WGM * nN, gid = wgid / nig, fm = gid * WGM, gsz = (nM - fm) < WGM ? (nM - fm) : WGM;
;         u.pm = fm + ((wgid % nig) % gsz); u.pn = (wgid % nig) / gsz; return true;
;     }
.LBB0_751:
	s_ashr_i32 s6, s22, 3
	s_add_i32 s6, s25, s6
	s_ashr_i32 s7, s6, 31
	s_lshr_b32 s7, s7, 28
	s_add_i32 s7, s6, s7
	s_ashr_i32 s22, s7, 4
	s_lshl_b32 s22, s22, 2
	s_sub_i32 s23, 0x80, s22
	s_min_i32 s23, s23, 4
	s_and_b32 s7, s7, -16
	s_sub_i32 s6, s6, s7
	s_lshr_b32 s58, s6, 2
	s_and_b32 s6, s6, 3
	s_add_i32 s59, s22, s6

;     __host__ __device__ bool next(int i, Unit& u) const {
;         const long L = (long)i * G + c; if (L >= nwg) return false;
;         int wgid = (int)L; { const int q = nwg / NXCD, r = nwg % NXCD, xcd = wgid % NXCD, off = wgid / NXCD; wgid = (xcd < r ? xcd * (q + 1) : r * (q + 1) + (xcd - r) * q) + off; }
;         const int nig = WGM * nN, gid = wgid / nig, fm = gid * WGM, gsz = (nM - fm) < WGM ? (nM - fm) : WGM;
;         u.pm = fm + ((wgid % nig) % gsz); u.pn = (wgid % nig) / gsz; return true;
;     }
.LBB0_848:
	s_ashr_i32 s7, s7, 3
	s_add_i32 s7, s25, s7
	s_ashr_i32 s22, s7, 31
	s_lshr_b32 s22, s22, 28
	s_add_i32 s22, s7, s22
	s_ashr_i32 s23, s22, 4
	s_lshl_b32 s23, s23, 2
	s_sub_i32 s24, 0x80, s23
	s_min_i32 s24, s24, 4
	s_and_b32 s22, s22, -16
	s_sub_i32 s7, s7, s22
	s_lshr_b32 s36, s7, 2
	s_and_b32 s7, s7, 3
	s_add_i32 s40, s23, s7

;     __host__ __device__ bool next(int i, Unit& u) const {
;         const long L = (long)i * G + c; if (L >= nwg) return false;
;         int wgid = (int)L; { const int q = nwg / NXCD, r = nwg % NXCD, xcd = wgid % NXCD, off = wgid / NXCD; wgid = (xcd < r ? xcd * (q + 1) : r * (q + 1) + (xcd - r) * q) + off; }
;         const int nig = WGM * nN, gid = wgid / nig, fm = gid * WGM, gsz = (nM - fm) < WGM ? (nM - fm) : WGM;
;         u.pm = fm + ((wgid % nig) % gsz); u.pn = (wgid % nig) / gsz; return true;
;     }
.LBB0_1044:
	s_ashr_i32 s22, s24, 3
	s_add_i32 s22, s26, s22
	s_ashr_i32 s23, s22, 31
	s_lshr_b32 s23, s23, 28
	s_add_i32 s23, s22, s23
	s_ashr_i32 s24, s23, 4
	s_lshl_b32 s24, s24, 2
	s_sub_i32 s25, 0x80, s24
	s_min_i32 s25, s25, 4
	s_and_b32 s23, s23, -16
	s_sub_i32 s22, s22, s23
	s_lshr_b32 s40, s22, 2
	s_and_b32 s22, s22, 3
	s_add_i32 s42, s24, s22
	s_andn2_b64 vcc, exec, s[8:9]
	s_mov_b64 s[8:9], -1
	s_cbranch_vccnz .LBB0_1015

;     __host__ __device__ bool next(int i, Unit& u) const {
;         const long L = (long)i * G + c; if (L >= nwg) return false;
;         int wgid = (int)L; { const int q = nwg / NXCD, r = nwg % NXCD, xcd = wgid % NXCD, off = wgid / NXCD; wgid = (xcd < r ? xcd * (q + 1) : r * (q + 1) + (xcd - r) * q) + off; }
;         const int nig = WGM * nN, gid = wgid / nig, fm = gid * WGM, gsz = (nM - fm) < WGM ? (nM - fm) : WGM;
;         u.pm = fm + ((wgid % nig) % gsz); u.pn = (wgid % nig) / gsz; return true;
;     }
.LBB0_1108:
	s_add_i32 s49, s49, 1
	s_mul_i32 s2, s49, s52
	s_mul_hi_u32 s3, s49, s53
	s_add_i32 s3, s3, s2
	s_mul_i32 s2, s49, s53
	v_readlane_b32 s15, v239, 0
	s_add_u32 s18, s2, s15
	s_addc_u32 s19, s3, s43
	v_cmp_gt_i64_e32 vcc, s[18:19], v[144:145]
	v_cmp_lt_i64_e64 s[2:3], s[18:19], v[142:143]
	s_cbranch_vccnz .LBB0_1110
	s_ashr_i32 s14, s18, 31
	s_lshr_b32 s14, s14, 29
	s_add_i32 s14, s18, s14
	s_ashr_i32 s15, s14, 3
	s_and_b32 s14, s14, -8
	s_sub_i32 s14, s18, s14
	s_cmp_lt_i32 s14, 0
	s_cselect_b32 s16, s44, 0x160
	s_mul_i32 s14, s14, s16
	s_add_i32 s14, s14, s15
	s_mul_hi_i32 s15, s14, 0x2e8ba2e9
	s_lshr_b32 s16, s15, 31
	s_ashr_i32 s15, s15, 4
	s_add_i32 s15, s15, s16
	s_lshl_b32 s16, s15, 2
	s_sub_i32 s17, 0x80, s16
	s_min_i32 s17, s17, 4
	s_mulk_i32 s15, 0x58
	s_sub_i32 s15, s14, s15
	s_lshr_b32 s14, s15, 2
	s_and_b32 s15, s15, 3
	s_add_i32 s16, s16, s15
